# attention PV MFMA order: same-accumulator pairs (o0,o0,o1,o1,...) with the first-half V wait recounted
# speedup vs baseline: 1.0041x; 1.0032x over previous
.LBB0_91:
	s_waitcnt lgkmcnt(14)
	v_mfma_f32_32x32x16_bf16 v[32:47], v[164:167], v[208:211], v[32:47]
	v_exp_f32_e32 v128, v128
	v_exp_f32_e32 v129, v129
	ds_read_b64_tr_b16 v[92:93], v213 offset:32768
	ds_read_b64_tr_b16 v[94:95], v213 offset:33280
	s_waitcnt lgkmcnt(12)
	v_mfma_f32_32x32x16_bf16 v[32:47], v[156:159], v[96:99], v[32:47]
	v_exp_f32_e32 v130, v130
	v_exp_f32_e32 v131, v131
	ds_read_b64_tr_b16 v[96:97], v213 offset:33792
	ds_read_b64_tr_b16 v[98:99], v213 offset:34304
	v_add_u32_e32 v176, s25, v224
	ds_read_b128 v[80:83], v176
	ds_read_b128 v[196:199], v176 offset:512
	s_waitcnt lgkmcnt(14)
	v_mfma_f32_32x32x16_bf16 v[48:63], v[164:167], v[204:207], v[48:63]
	v_exp_f32_e32 v132, v132
	v_exp_f32_e32 v133, v133
	ds_read_b64_tr_b16 v[204:205], v213 offset:36864
	ds_read_b64_tr_b16 v[206:207], v213 offset:37376
	ds_read_b128 v[200:203], v176 offset:2048
	ds_read_b128 v[192:195], v176 offset:2560
	v_mfma_f32_32x32x16_bf16 v[48:63], v[156:159], v[100:103], v[48:63]
	v_exp_f32_e32 v134, v134
	v_exp_f32_e32 v135, v135
	ds_read_b64_tr_b16 v[100:101], v213 offset:37888
	ds_read_b64_tr_b16 v[102:103], v213 offset:38400
	ds_read_b128 v[188:191], v176 offset:4096
	ds_read_b128 v[184:187], v176 offset:4608
	s_waitcnt lgkmcnt(14)
	v_mfma_f32_32x32x16_bf16 v[32:47], v[148:151], v[104:107], v[32:47]
	v_exp_f32_e32 v136, v136
	v_exp_f32_e32 v137, v137
	ds_read_b64_tr_b16 v[104:105], v213 offset:34816
	ds_read_b64_tr_b16 v[106:107], v213 offset:35328
	ds_read_b128 v[180:183], v176 offset:6144
	ds_read_b128 v[176:179], v176 offset:6656
	v_mfma_f32_32x32x16_bf16 v[32:47], v[144:147], v[84:87], v[32:47]
	v_exp_f32_e32 v138, v138
	v_exp_f32_e32 v139, v139
	ds_read_b64_tr_b16 v[84:85], v213 offset:35840
	ds_read_b64_tr_b16 v[86:87], v213 offset:36352
	v_mfma_f32_32x32x16_bf16 v[48:63], v[148:151], v[108:111], v[48:63]
	v_exp_f32_e32 v140, v140
	v_exp_f32_e32 v141, v141
	ds_read_b64_tr_b16 v[108:109], v213 offset:38912
	ds_read_b64_tr_b16 v[110:111], v213 offset:39424
	v_mfma_f32_32x32x16_bf16 v[48:63], v[144:147], v[88:91], v[48:63]
	v_exp_f32_e32 v142, v142
	v_exp_f32_e32 v143, v143
	ds_read_b64_tr_b16 v[88:89], v213 offset:39936
	ds_read_b64_tr_b16 v[90:91], v213 offset:40448
	s_waitcnt lgkmcnt(14)
	v_mfma_f32_32x32x16_bf16 v[16:31], v[164:167], v[92:95], v[16:31]
	v_exp_f32_e32 v112, v112
	v_exp_f32_e32 v113, v113
	v_mfma_f32_32x32x16_bf16 v[16:31], v[156:159], v[96:99], v[16:31]
	v_exp_f32_e32 v114, v114
	v_exp_f32_e32 v115, v115
	v_mfma_f32_32x32x16_bf16 v[0:15], v[164:167], v[204:207], v[0:15]
	v_exp_f32_e32 v116, v116
	v_exp_f32_e32 v117, v117
	s_waitcnt lgkmcnt(12)
	v_mfma_f32_32x32x16_bf16 v[0:15], v[156:159], v[100:103], v[0:15]
	v_exp_f32_e32 v118, v118
	v_exp_f32_e32 v119, v119
	s_waitcnt lgkmcnt(8)
	v_mfma_f32_32x32x16_bf16 v[16:31], v[148:151], v[104:107], v[16:31]
	v_exp_f32_e32 v120, v120
	v_exp_f32_e32 v121, v121
	s_waitcnt lgkmcnt(4)
	v_mfma_f32_32x32x16_bf16 v[16:31], v[144:147], v[84:87], v[16:31]
	v_exp_f32_e32 v122, v122
	v_exp_f32_e32 v123, v123
	s_waitcnt lgkmcnt(2)
	v_mfma_f32_32x32x16_bf16 v[0:15], v[148:151], v[108:111], v[0:15]
	v_exp_f32_e32 v124, v124
	v_exp_f32_e32 v125, v125
	s_waitcnt lgkmcnt(0)
	v_mfma_f32_32x32x16_bf16 v[0:15], v[144:147], v[88:91], v[0:15]
	v_exp_f32_e32 v126, v126
	v_exp_f32_e32 v127, v127
	s_waitcnt vmcnt(3) lgkmcnt(0)
	s_barrier
	s_andn2_b64 vcc, exec, s[38:39]
	v_add_u32_e32 v213, s17, v226
	s_cbranch_vccnz .LBB0_93
	s_waitcnt lgkmcnt(0)
	ds_read_b128 v[84:87], v213 offset:96
	ds_read_b128 v[88:91], v213 offset:64
	ds_read_b128 v[92:95], v213 offset:32
	ds_read_b128 v[96:99], v213
	s_waitcnt lgkmcnt(3)
	v_pk_mul_f32 v[44:45], v[44:45], v[84:85]
	s_waitcnt lgkmcnt(2)
	v_pk_mul_f32 v[40:41], v[40:41], v[88:89]
	s_waitcnt lgkmcnt(1)
	v_pk_mul_f32 v[36:37], v[36:37], v[92:93]
	v_pk_mul_f32 v[46:47], v[46:47], v[86:87]
	v_pk_mul_f32 v[42:43], v[42:43], v[90:91]
	v_pk_mul_f32 v[38:39], v[38:39], v[94:95]
	s_waitcnt lgkmcnt(0)
	v_pk_mul_f32 v[34:35], v[34:35], v[98:99]
	v_pk_mul_f32 v[32:33], v[32:33], v[96:97]
	v_pk_mul_f32 v[60:61], v[60:61], v[84:85]
	v_pk_mul_f32 v[56:57], v[56:57], v[88:89]
	v_pk_mul_f32 v[52:53], v[52:53], v[92:93]
	v_pk_mul_f32 v[62:63], v[62:63], v[86:87]
	v_pk_mul_f32 v[58:59], v[58:59], v[90:91]
	v_pk_mul_f32 v[54:55], v[54:55], v[94:95]
	v_pk_mul_f32 v[50:51], v[50:51], v[98:99]
	v_pk_mul_f32 v[48:49], v[48:49], v[96:97]
	v_pk_mul_f32 v[28:29], v[28:29], v[84:85]
	v_pk_mul_f32 v[24:25], v[24:25], v[88:89]
	v_pk_mul_f32 v[20:21], v[20:21], v[92:93]
	v_pk_mul_f32 v[30:31], v[30:31], v[86:87]
	v_pk_mul_f32 v[26:27], v[26:27], v[90:91]
	v_pk_mul_f32 v[22:23], v[22:23], v[94:95]
	v_pk_mul_f32 v[18:19], v[18:19], v[98:99]
	v_pk_mul_f32 v[16:17], v[16:17], v[96:97]
	v_pk_mul_f32 v[12:13], v[12:13], v[84:85]
	v_pk_mul_f32 v[8:9], v[8:9], v[88:89]
	v_pk_mul_f32 v[4:5], v[4:5], v[92:93]
	v_pk_mul_f32 v[14:15], v[14:15], v[86:87]
	v_pk_mul_f32 v[10:11], v[10:11], v[90:91]
	v_pk_mul_f32 v[6:7], v[6:7], v[94:95]
	v_pk_mul_f32 v[2:3], v[2:3], v[98:99]
	v_pk_mul_f32 v[0:1], v[0:1], v[96:97]

.LBB0_94:
	s_waitcnt lgkmcnt(14)
	v_mfma_f32_32x32x16_bf16 v[32:47], v[164:167], v[204:207], v[32:47]
	v_exp_f32_e32 v96, v96
	v_exp_f32_e32 v97, v97
	ds_read_b64_tr_b16 v[124:125], v228 offset:32768
	ds_read_b64_tr_b16 v[126:127], v228 offset:33280
	s_waitcnt lgkmcnt(12)
	v_mfma_f32_32x32x16_bf16 v[32:47], v[156:159], v[128:131], v[32:47]
	v_exp_f32_e32 v98, v98
	v_exp_f32_e32 v99, v99
	ds_read_b64_tr_b16 v[128:129], v228 offset:33792
	ds_read_b64_tr_b16 v[130:131], v228 offset:34304
	v_add_u32_e32 v176, s21, v224
	ds_read_b128 v[204:207], v176
	ds_read_b128 v[200:203], v176 offset:512
	s_waitcnt lgkmcnt(14)
	v_mfma_f32_32x32x16_bf16 v[48:63], v[164:167], v[208:211], v[48:63]
	v_exp_f32_e32 v100, v100
	v_exp_f32_e32 v101, v101
	ds_read_b64_tr_b16 v[140:141], v228 offset:36864
	ds_read_b64_tr_b16 v[142:143], v228 offset:37376
	ds_read_b128 v[196:199], v176 offset:2048
	ds_read_b128 v[192:195], v176 offset:2560
	v_mfma_f32_32x32x16_bf16 v[48:63], v[156:159], v[132:135], v[48:63]
	v_exp_f32_e32 v102, v102
	v_exp_f32_e32 v103, v103
	ds_read_b64_tr_b16 v[132:133], v228 offset:37888
	ds_read_b64_tr_b16 v[134:135], v228 offset:38400
	ds_read_b128 v[188:191], v176 offset:4096
	ds_read_b128 v[184:187], v176 offset:4608
	s_waitcnt lgkmcnt(14)
	v_mfma_f32_32x32x16_bf16 v[32:47], v[148:151], v[136:139], v[32:47]
	v_exp_f32_e32 v104, v104
	v_exp_f32_e32 v105, v105
	ds_read_b64_tr_b16 v[136:137], v228 offset:34816
	ds_read_b64_tr_b16 v[138:139], v228 offset:35328
	ds_read_b128 v[180:183], v176 offset:6144
	ds_read_b128 v[176:179], v176 offset:6656
	v_mfma_f32_32x32x16_bf16 v[32:47], v[144:147], v[116:119], v[32:47]
	v_exp_f32_e32 v106, v106
	v_exp_f32_e32 v107, v107
	ds_read_b64_tr_b16 v[116:117], v228 offset:35840
	ds_read_b64_tr_b16 v[118:119], v228 offset:36352
	v_mfma_f32_32x32x16_bf16 v[48:63], v[148:151], v[112:115], v[48:63]
	v_exp_f32_e32 v108, v108
	v_exp_f32_e32 v109, v109
	ds_read_b64_tr_b16 v[112:113], v228 offset:38912
	ds_read_b64_tr_b16 v[114:115], v228 offset:39424
	v_mfma_f32_32x32x16_bf16 v[48:63], v[144:147], v[120:123], v[48:63]
	v_exp_f32_e32 v110, v110
	v_exp_f32_e32 v111, v111
	ds_read_b64_tr_b16 v[120:121], v228 offset:39936
	ds_read_b64_tr_b16 v[122:123], v228 offset:40448
	s_waitcnt lgkmcnt(14)
	v_mfma_f32_32x32x16_bf16 v[16:31], v[164:167], v[124:127], v[16:31]
	v_exp_f32_e32 v80, v80
	v_exp_f32_e32 v81, v81
	v_mfma_f32_32x32x16_bf16 v[16:31], v[156:159], v[128:131], v[16:31]
	v_exp_f32_e32 v82, v82
	v_exp_f32_e32 v83, v83
	v_mfma_f32_32x32x16_bf16 v[0:15], v[164:167], v[140:143], v[0:15]
	v_exp_f32_e32 v84, v84
	v_exp_f32_e32 v85, v85
	s_waitcnt lgkmcnt(12)
	v_mfma_f32_32x32x16_bf16 v[0:15], v[156:159], v[132:135], v[0:15]
	v_exp_f32_e32 v86, v86
	v_exp_f32_e32 v87, v87
	s_waitcnt lgkmcnt(8)
	v_mfma_f32_32x32x16_bf16 v[16:31], v[148:151], v[136:139], v[16:31]
	v_exp_f32_e32 v88, v88
	v_exp_f32_e32 v89, v89
	s_waitcnt lgkmcnt(4)
	v_mfma_f32_32x32x16_bf16 v[16:31], v[144:147], v[116:119], v[16:31]
	v_exp_f32_e32 v90, v90
	v_exp_f32_e32 v91, v91
	s_waitcnt lgkmcnt(2)
	v_mfma_f32_32x32x16_bf16 v[0:15], v[148:151], v[112:115], v[0:15]
	v_exp_f32_e32 v92, v92
	v_exp_f32_e32 v93, v93
	s_waitcnt lgkmcnt(0)
	v_mfma_f32_32x32x16_bf16 v[0:15], v[144:147], v[120:123], v[0:15]
	v_exp_f32_e32 v94, v94
	v_exp_f32_e32 v95, v95
	s_waitcnt vmcnt(3) lgkmcnt(0)
	s_barrier
	s_andn2_b64 vcc, exec, s[38:39]
	s_cbranch_vccnz .LBB0_96
	s_waitcnt lgkmcnt(0)
	ds_read_b128 v[112:115], v213 offset:96
	ds_read_b128 v[116:119], v213 offset:64
	ds_read_b128 v[120:123], v213 offset:32
	ds_read_b128 v[124:127], v213
	s_waitcnt lgkmcnt(3)
	v_pk_mul_f32 v[44:45], v[44:45], v[112:113]
	s_waitcnt lgkmcnt(2)
	v_pk_mul_f32 v[40:41], v[40:41], v[116:117]
	s_waitcnt lgkmcnt(1)
	v_pk_mul_f32 v[36:37], v[36:37], v[120:121]
	v_pk_mul_f32 v[46:47], v[46:47], v[114:115]
	v_pk_mul_f32 v[42:43], v[42:43], v[118:119]
	v_pk_mul_f32 v[38:39], v[38:39], v[122:123]
	s_waitcnt lgkmcnt(0)
	v_pk_mul_f32 v[34:35], v[34:35], v[126:127]
	v_pk_mul_f32 v[32:33], v[32:33], v[124:125]
	v_pk_mul_f32 v[60:61], v[60:61], v[112:113]
	v_pk_mul_f32 v[56:57], v[56:57], v[116:117]
	v_pk_mul_f32 v[52:53], v[52:53], v[120:121]
	v_pk_mul_f32 v[62:63], v[62:63], v[114:115]
	v_pk_mul_f32 v[58:59], v[58:59], v[118:119]
	v_pk_mul_f32 v[54:55], v[54:55], v[122:123]
	v_pk_mul_f32 v[50:51], v[50:51], v[126:127]
	v_pk_mul_f32 v[48:49], v[48:49], v[124:125]
	v_pk_mul_f32 v[28:29], v[28:29], v[112:113]
	v_pk_mul_f32 v[24:25], v[24:25], v[116:117]
	v_pk_mul_f32 v[20:21], v[20:21], v[120:121]
	v_pk_mul_f32 v[30:31], v[30:31], v[114:115]
	v_pk_mul_f32 v[26:27], v[26:27], v[118:119]
	v_pk_mul_f32 v[22:23], v[22:23], v[122:123]
	v_pk_mul_f32 v[18:19], v[18:19], v[126:127]
	v_pk_mul_f32 v[16:17], v[16:17], v[124:125]
	v_pk_mul_f32 v[12:13], v[12:13], v[112:113]
	v_pk_mul_f32 v[8:9], v[8:9], v[116:117]
	v_pk_mul_f32 v[4:5], v[4:5], v[120:121]
	v_pk_mul_f32 v[14:15], v[14:15], v[114:115]
	v_pk_mul_f32 v[10:11], v[10:11], v[118:119]
	v_pk_mul_f32 v[6:7], v[6:7], v[122:123]
	v_pk_mul_f32 v[2:3], v[2:3], v[126:127]
	v_pk_mul_f32 v[0:1], v[0:1], v[124:125]
